# FFN RMSNorm fused into the attention-output GEMM epilogue (k8 phase emptied, its second barrier skipped) + final-norm fusion
# baseline (speedup 1.0000x reference)
; __device__ __forceinline__ int tid_opaque() { int t; asm volatile("v_mov_b32 %0, %1" : "=v"(t) : "v"((int)threadIdx.x)); __builtin_assume(t >= 0 && t < NTHREADS); return t; }
; __device__ __forceinline__ int bid_opaque() { int t; asm volatile("s_mov_b32 %0, %1" : "=s"(t) : "s"((int)blockIdx.x)); __builtin_assume(t >= 0 && t < 1024); return t; }
; __global__ void __launch_bounds__(NTHREADS, 2) mega(Args a_unused) {
;     ...
;     for (int p = plo; p < phi; ++p) {
;         unsigned char* ws = a.ws();
;         if (p == plo + 1) grid.sync();
;         else if (p > plo) xcd_barrier(xbar);
;         const int tid = tid_opaque(), lane = tid & 63, wave = __builtin_amdgcn_readfirstlane(tid >> 6);
;         const int gw = bid_opaque() * NWAVES + wave, ngw = gridDim.x * NWAVES;
.LBB0_10:
	s_waitcnt vmcnt(0)
	ds_read_b64 v[2:3], v193
	v_readlane_b32 s0, v253, 6
	v_writelane_b32 v255, s1, 12
	s_cmp_lg_u32 s1, s0
	s_mov_b64 s[2:3], 0
	s_waitcnt lgkmcnt(0)
	v_readfirstlane_b32 s1, v3
	v_readfirstlane_b32 s0, v2
	s_nop 1
	v_writelane_b32 v255, s0, 13
	s_nop 1
	v_writelane_b32 v255, s1, 14
	s_mov_b64 s[0:1], -1
	s_nop 0
	v_readlane_b32 s2, v253, 4
	v_readlane_b32 s3, v255, 12
	s_mov_b64 s[0:1], 0
	s_cmp_gt_i32 s3, s2
	s_mov_b64 s[2:3], 0
	s_cbranch_scc0 .LBB0_57
	v_readlane_b32 s98, v255, 12
	s_cmp_eq_u32 s98, 10
	s_cbranch_scc1 .LBB0_57
	s_cmp_eq_u32 s98, 22
	s_cbranch_scc1 .LBB0_57
	s_cmp_eq_u32 s98, 34
	s_cbranch_scc1 .LBB0_57
	s_cmp_eq_u32 s98, 46
	s_cbranch_scc1 .LBB0_57
	s_waitcnt vmcnt(0)
	s_barrier
	s_mov_b64 s[2:3], exec
	v_readlane_b32 s4, v253, 2
	v_readlane_b32 s5, v253, 3
	s_and_b64 s[4:5], s[2:3], s[4:5]
	s_mov_b64 exec, s[4:5]
	s_cbranch_execz .LBB0_56
	v_readlane_b32 s4, v254, 20
	s_waitcnt vmcnt(0) expcnt(0) lgkmcnt(0)
	s_nop 0
	v_mov_b32_e32 v0, s4
	ds_read_b32 v2, v0
	v_readlane_b32 s4, v254, 21
	s_waitcnt lgkmcnt(0)
	v_cmp_ne_u32_e32 vcc, 0, v2
	v_mov_b32_e32 v0, s4
	ds_read_b32 v0, v0
	s_cbranch_vccnz .LBB0_27
	s_mov_b32 s12, 1
	s_mov_b64 s[4:5], 0
	s_branch .LBB0_17

;     __device__ __forceinline__ const void* in(int i) const { return (const void*)uni64(t[i]); }
;     __device__ __forceinline__ float* out() const { return (float*)uni64(t[33]); }
; __device__ __forceinline__ void rmsnorm_rows(const float* x, const float* gain, bf16_t* o, int nrows, int gw, int ngw, int lane) {
;     f32x4 gv[4];
; #pragma unroll
;     for (int j = 0; j < 4; ++j) gv[j] = ldg<f32x4>((const f32x4*)gain + lane + 64 * j);
; #pragma unroll 1
;     for (int r = gw; r < nrows; r += 2 * ngw) {
;         const int r2 = r + ngw; const bool has2 = r2 < nrows; const int rb = has2 ? r2 : r;
; __global__ void __launch_bounds__(NTHREADS, 2) mega(Args a_unused) {
;     ...
;         case 8: rmsnorm_rows(a.out() + (size_t)grp * TG * D, (const float*)a.in(I_NFFN) + l * D, (bf16_t*)(ws + WS_HB), TG, gw, ngw, lane); break;
.LBB0_97:
	s_and_b64 vcc, exec, s[0:1]
	s_cbranch_vccz .LBB0_108
	s_and_b32 s0, 0xffff, s76
	s_cmp_eq_u32 s0, 8
	s_mov_b64 s[92:93], -1
	s_cbranch_scc0 .LBB0_108
	v_readlane_b32 s0, v254, 23
	v_readlane_b32 s2, v254, 26
	s_cmpk_gt_u32 s18, 0x3fff
	v_mov_b32_e32 v0, s0
	ds_read_b64 v[2:3], v0
	v_mov_b32_e32 v0, s2
	s_waitcnt lgkmcnt(0)
	v_readfirstlane_b32 s0, v3
	v_readfirstlane_b32 s1, v2
	ds_read_b64 v[2:3], v0
	s_waitcnt lgkmcnt(0)
	v_readfirstlane_b32 s2, v3
	v_readfirstlane_b32 s3, v2
	s_branch .LBB0_107
	s_lshl_b32 s4, s94, 10
	s_ashr_i32 s5, s4, 31
	s_lshl_b64 s[4:5], s[4:5], 2
	s_add_u32 s4, s3, s4
	s_addc_u32 s5, s2, s5
	v_lshlrev_b32_e32 v0, 4, v178
	global_load_dwordx4 v[2:5], v0, s[4:5] offset:3072
	global_load_dwordx4 v[6:9], v0, s[4:5] offset:2048
	global_load_dwordx4 v[10:13], v0, s[4:5] offset:1024
	global_load_dwordx4 v[14:17], v0, s[4:5]
	s_ashr_i32 s91, s90, 31
	s_lshl_b64 s[2:3], s[90:91], 26
	s_add_u32 s2, s1, s2
	s_addc_u32 s3, s0, s3
	v_lshl_add_u64 v[34:35], s[2:3], 0, v[0:1]
	v_and_b32_e32 v0, 64, v196
	v_readlane_b32 s0, v255, 13
	v_add_u32_e32 v20, 64, v0
	v_lshlrev_b32_e32 v0, 3, v178
	v_readlane_b32 s1, v255, 14
	s_mov_b32 s2, s18
	s_nop 0
	v_lshl_add_u64 v[18:19], s[0:1], 0, v[0:1]
	s_mov_b64 s[0:1], 0x2d00000
	v_xor_b32_e32 v0, 1, v196
	v_lshl_add_u64 v[36:37], v[18:19], 0, s[0:1]
	v_cmp_lt_i32_e32 vcc, v0, v20
	v_xor_b32_e32 v18, 2, v196
	s_nop 0
	v_cndmask_b32_e32 v0, v196, v0, vcc
	v_cmp_lt_i32_e32 vcc, v18, v20
	v_lshlrev_b32_e32 v0, 2, v0
	s_nop 0
	v_cndmask_b32_e32 v18, v196, v18, vcc
	v_lshlrev_b32_e32 v38, 2, v18
	v_xor_b32_e32 v18, 4, v196
	v_cmp_lt_i32_e32 vcc, v18, v20
	s_nop 1
	v_cndmask_b32_e32 v18, v196, v18, vcc
	v_lshlrev_b32_e32 v39, 2, v18
	v_xor_b32_e32 v18, 8, v196
	v_cmp_lt_i32_e32 vcc, v18, v20
	s_nop 1
	v_cndmask_b32_e32 v18, v196, v18, vcc
	v_lshlrev_b32_e32 v40, 2, v18
	v_xor_b32_e32 v18, 16, v196
	v_cmp_lt_i32_e32 vcc, v18, v20
	s_nop 1
	v_cndmask_b32_e32 v18, v196, v18, vcc
	v_lshlrev_b32_e32 v41, 2, v18
	v_xor_b32_e32 v18, 32, v196
	v_cmp_lt_i32_e32 vcc, v18, v20
	s_nop 1
	v_cndmask_b32_e32 v18, v196, v18, vcc
	v_lshlrev_b32_e32 v42, 2, v18
	s_branch .LBB0_105

;     __device__ __forceinline__ float* out() const { return (float*)uni64(t[33]); }
;     __device__ __forceinline__ void emit(int row, int pn, int col0, float* v) const {
;     ...
;         case K_WO: case K_DN: {
;             const size_t o = ((size_t)grp * TG + row) * D + col0;
;             const f32x4 a0 = ldg<f32x4>(xi + o), a1 = ldg<f32x4>(xi + o + 4);
;             f32x4 r0, r1; r0.x = a0.x + v[0]; r0.y = a0.y + v[1]; r0.z = a0.z + v[2]; r0.w = a0.w + v[3]; r1.x = a1.x + v[4]; r1.y = a1.y + v[5]; r1.z = a1.z + v[6]; r1.w = a1.w + v[7];
;             stg<f32x4>(xo + o, r0); stg<f32x4>(xo + o + 4, r1);
; __global__ void __launch_bounds__(NTHREADS, 2) mega(Args a_unused) {
;     ...
;             case 7: E.kind = K_WO; E.xi = xin; E.xo = a.out(); boff = WT_O; N = 1024; break;
;             case 9: break;
;             default: E.kind = K_DN; E.xi = a.out(); E.xo = a.out(); aoff = WS_ACT; lda = DFF; boff = WT_DN; N = 1024; K = DFF; break;
.LBB0_462:
	s_cmp_eq_u32 s28, 5
	s_cbranch_scc1 .Lwo_epi
	s_cmp_eq_u32 s28, 7
	s_cbranch_scc0 .Lfx_no
	v_readlane_b32 s98, v255, 12
	s_cmpk_gt_u32 s98, 24
	s_cbranch_scc1 .Lfn_epi

; __device__ __forceinline__ void rmsnorm_rows_f32(float* x, const float* gain, int nrows, int gw, int ngw, int lane) {
;     ...
;         f32x4* xr = (f32x4*)(x + (size_t)r * D) + lane; f32x4 v[4]; float s = 0.f;
; #pragma unroll
;         for (int j = 0; j < 4; ++j) { v[j] = xr[64 * j]; s += (v[j].x * v[j].x + v[j].y * v[j].y) + (v[j].z * v[j].z + v[j].w * v[j].w); }
;         const float rs = rsqrtf(wave_sum(s) * (1.f / D) + 1e-6f);
; #pragma unroll
;         for (int j = 0; j < 4; ++j) xr[64 * j] = v[j] * rs * gv[j];
.Lfn_bw:
	s_barrier
	v_lshlrev_b32_e32 v136, 2, v202
	v_add_u32_e32 v137, 0x10000, v136
	v_add_u32_e32 v138, 0x20000, v136
	v_add_u32_e32 v139, 0x30000, v136
	global_load_dword v210, v136, s[98:99] sc1
	global_load_dword v211, v137, s[98:99] sc1
	global_load_dword v212, v138, s[98:99] sc1
	global_load_dword v213, v139, s[98:99] sc1
	global_load_dword v214, v136, s[98:99] offset:64 sc1
	global_load_dword v215, v137, s[98:99] offset:64 sc1
	global_load_dword v216, v138, s[98:99] offset:64 sc1
	global_load_dword v217, v139, s[98:99] offset:64 sc1
	global_load_dword v218, v136, s[98:99] offset:128 sc1
	global_load_dword v219, v137, s[98:99] offset:128 sc1
	global_load_dword v220, v138, s[98:99] offset:128 sc1
	global_load_dword v221, v139, s[98:99] offset:128 sc1
	global_load_dword v222, v136, s[98:99] offset:192 sc1
	global_load_dword v223, v137, s[98:99] offset:192 sc1
	global_load_dword v224, v138, s[98:99] offset:192 sc1
	global_load_dword v225, v139, s[98:99] offset:192 sc1
	global_load_dword v226, v136, s[98:99] offset:512 sc1
	global_load_dword v227, v137, s[98:99] offset:512 sc1
	global_load_dword v228, v138, s[98:99] offset:512 sc1
	global_load_dword v229, v139, s[98:99] offset:512 sc1
	global_load_dword v230, v136, s[98:99] offset:576 sc1
	global_load_dword v231, v137, s[98:99] offset:576 sc1
	global_load_dword v232, v138, s[98:99] offset:576 sc1
	global_load_dword v233, v139, s[98:99] offset:576 sc1
	global_load_dword v234, v136, s[98:99] offset:640 sc1
	global_load_dword v235, v137, s[98:99] offset:640 sc1
	global_load_dword v236, v138, s[98:99] offset:640 sc1
	global_load_dword v237, v139, s[98:99] offset:640 sc1
	global_load_dword v238, v136, s[98:99] offset:704 sc1
	global_load_dword v239, v137, s[98:99] offset:704 sc1
	global_load_dword v240, v138, s[98:99] offset:704 sc1
	global_load_dword v241, v139, s[98:99] offset:704 sc1
	v_mov_b32_e32 v0, 0x25940
	ds_read_b64 v[140:141], v0
	v_lshlrev_b32_e32 v0, 2, v203
	v_mov_b32_e32 v142, 0x358637bd
	s_waitcnt lgkmcnt(0)
	v_readfirstlane_b32 s100, v140
	v_readfirstlane_b32 s101, v141
	s_nop 4
	global_load_dwordx4 v[144:147], v0, s[100:101]
	global_load_dwordx4 v[148:151], v0, s[100:101] offset:16
	global_load_dwordx4 v[152:155], v0, s[100:101] offset:512
	global_load_dwordx4 v[156:159], v0, s[100:101] offset:528
	s_waitcnt vmcnt(0)
	v_add_f32_e32 v210, v210, v211
	v_add_f32_e32 v210, v210, v212
	v_add_f32_e32 v210, v210, v213
	v_fmamk_f32 v210, v210, 0x3a800000, v142
	v_add_f32_e32 v214, v214, v215
	v_add_f32_e32 v214, v214, v216
	v_add_f32_e32 v214, v214, v217
	v_fmamk_f32 v214, v214, 0x3a800000, v142
	v_add_f32_e32 v218, v218, v219
	v_add_f32_e32 v218, v218, v220
	v_add_f32_e32 v218, v218, v221
	v_fmamk_f32 v218, v218, 0x3a800000, v142
	v_add_f32_e32 v222, v222, v223
	v_add_f32_e32 v222, v222, v224
	v_add_f32_e32 v222, v222, v225
	v_fmamk_f32 v222, v222, 0x3a800000, v142
	v_add_f32_e32 v226, v226, v227
	v_add_f32_e32 v226, v226, v228
	v_add_f32_e32 v226, v226, v229
	v_fmamk_f32 v226, v226, 0x3a800000, v142
	v_add_f32_e32 v230, v230, v231
	v_add_f32_e32 v230, v230, v232
	v_add_f32_e32 v230, v230, v233
	v_fmamk_f32 v230, v230, 0x3a800000, v142
	v_add_f32_e32 v234, v234, v235
	v_add_f32_e32 v234, v234, v236
	v_add_f32_e32 v234, v234, v237
	v_fmamk_f32 v234, v234, 0x3a800000, v142
	v_add_f32_e32 v238, v238, v239
	v_add_f32_e32 v238, v238, v240
	v_add_f32_e32 v238, v238, v241
	v_fmamk_f32 v238, v238, 0x3a800000, v142
	v_rsq_f32_e32 v210, v210
	v_rsq_f32_e32 v214, v214
	v_rsq_f32_e32 v218, v218
	v_rsq_f32_e32 v222, v222
	v_rsq_f32_e32 v226, v226
	v_rsq_f32_e32 v230, v230
	v_rsq_f32_e32 v234, v234
	v_rsq_f32_e32 v238, v238
	s_nop 0
	v_pk_mul_f32 v[128:129], v[128:129], v[210:211] op_sel_hi:[1,0]
	v_pk_mul_f32 v[130:131], v[130:131], v[210:211] op_sel_hi:[1,0]
	v_pk_mul_f32 v[124:125], v[124:125], v[210:211] op_sel_hi:[1,0]
	v_pk_mul_f32 v[126:127], v[126:127], v[210:211] op_sel_hi:[1,0]
	v_pk_mul_f32 v[128:129], v[144:145], v[128:129]
	v_pk_mul_f32 v[130:131], v[146:147], v[130:131]
	v_pk_mul_f32 v[124:125], v[148:149], v[124:125]
	v_pk_mul_f32 v[126:127], v[150:151], v[126:127]
	global_store_dwordx4 v182, v[128:131], s[66:67]
	global_store_dwordx4 v182, v[124:127], s[66:67] offset:16
	v_pk_mul_f32 v[120:121], v[120:121], v[210:211] op_sel_hi:[1,0]
	v_pk_mul_f32 v[122:123], v[122:123], v[210:211] op_sel_hi:[1,0]
	v_pk_mul_f32 v[116:117], v[116:117], v[210:211] op_sel_hi:[1,0]
	v_pk_mul_f32 v[118:119], v[118:119], v[210:211] op_sel_hi:[1,0]
	v_pk_mul_f32 v[120:121], v[152:153], v[120:121]
	v_pk_mul_f32 v[122:123], v[154:155], v[122:123]
	v_pk_mul_f32 v[116:117], v[156:157], v[116:117]
	v_pk_mul_f32 v[118:119], v[158:159], v[118:119]
	global_store_dwordx4 v182, v[120:123], s[66:67] offset:512
	global_store_dwordx4 v182, v[116:119], s[66:67] offset:528
	v_pk_mul_f32 v[112:113], v[112:113], v[214:215] op_sel_hi:[1,0]
	v_pk_mul_f32 v[114:115], v[114:115], v[214:215] op_sel_hi:[1,0]
	v_pk_mul_f32 v[108:109], v[108:109], v[214:215] op_sel_hi:[1,0]
	v_pk_mul_f32 v[110:111], v[110:111], v[214:215] op_sel_hi:[1,0]
	v_pk_mul_f32 v[112:113], v[144:145], v[112:113]
	v_pk_mul_f32 v[114:115], v[146:147], v[114:115]
	v_pk_mul_f32 v[108:109], v[148:149], v[108:109]
	v_pk_mul_f32 v[110:111], v[150:151], v[110:111]
	global_store_dwordx4 v183, v[112:115], s[66:67]
	global_store_dwordx4 v183, v[108:111], s[66:67] offset:16
	v_pk_mul_f32 v[104:105], v[104:105], v[214:215] op_sel_hi:[1,0]
	v_pk_mul_f32 v[106:107], v[106:107], v[214:215] op_sel_hi:[1,0]
	v_pk_mul_f32 v[100:101], v[100:101], v[214:215] op_sel_hi:[1,0]
	v_pk_mul_f32 v[102:103], v[102:103], v[214:215] op_sel_hi:[1,0]
	v_pk_mul_f32 v[104:105], v[152:153], v[104:105]
; __device__ __forceinline__ void rmsnorm_rows_f32(float* x, const float* gain, int nrows, int gw, int ngw, int lane) {
;     ...
; #pragma unroll
;         for (int j = 0; j < 4; ++j) xr[64 * j] = v[j] * rs * gv[j];
	v_pk_mul_f32 v[106:107], v[154:155], v[106:107]
	v_pk_mul_f32 v[100:101], v[156:157], v[100:101]
	v_pk_mul_f32 v[102:103], v[158:159], v[102:103]
	global_store_dwordx4 v183, v[104:107], s[66:67] offset:512
	global_store_dwordx4 v183, v[100:103], s[66:67] offset:528
	v_pk_mul_f32 v[96:97], v[96:97], v[218:219] op_sel_hi:[1,0]
	v_pk_mul_f32 v[98:99], v[98:99], v[218:219] op_sel_hi:[1,0]
	v_pk_mul_f32 v[92:93], v[92:93], v[218:219] op_sel_hi:[1,0]
	v_pk_mul_f32 v[94:95], v[94:95], v[218:219] op_sel_hi:[1,0]
	v_pk_mul_f32 v[96:97], v[144:145], v[96:97]
	v_pk_mul_f32 v[98:99], v[146:147], v[98:99]
	v_pk_mul_f32 v[92:93], v[148:149], v[92:93]
	v_pk_mul_f32 v[94:95], v[150:151], v[94:95]
	global_store_dwordx4 v184, v[96:99], s[66:67]
	global_store_dwordx4 v184, v[92:95], s[66:67] offset:16
	v_pk_mul_f32 v[88:89], v[88:89], v[218:219] op_sel_hi:[1,0]
	v_pk_mul_f32 v[90:91], v[90:91], v[218:219] op_sel_hi:[1,0]
	v_pk_mul_f32 v[84:85], v[84:85], v[218:219] op_sel_hi:[1,0]
	v_pk_mul_f32 v[86:87], v[86:87], v[218:219] op_sel_hi:[1,0]
	v_pk_mul_f32 v[88:89], v[152:153], v[88:89]
	v_pk_mul_f32 v[90:91], v[154:155], v[90:91]
	v_pk_mul_f32 v[84:85], v[156:157], v[84:85]
	v_pk_mul_f32 v[86:87], v[158:159], v[86:87]
	global_store_dwordx4 v184, v[88:91], s[66:67] offset:512
	global_store_dwordx4 v184, v[84:87], s[66:67] offset:528
	v_pk_mul_f32 v[80:81], v[80:81], v[222:223] op_sel_hi:[1,0]
	v_pk_mul_f32 v[82:83], v[82:83], v[222:223] op_sel_hi:[1,0]
	v_pk_mul_f32 v[76:77], v[76:77], v[222:223] op_sel_hi:[1,0]
	v_pk_mul_f32 v[78:79], v[78:79], v[222:223] op_sel_hi:[1,0]
	v_pk_mul_f32 v[80:81], v[144:145], v[80:81]
	v_pk_mul_f32 v[82:83], v[146:147], v[82:83]
	v_pk_mul_f32 v[76:77], v[148:149], v[76:77]
	v_pk_mul_f32 v[78:79], v[150:151], v[78:79]
	global_store_dwordx4 v185, v[80:83], s[66:67]
	global_store_dwordx4 v185, v[76:79], s[66:67] offset:16
	v_pk_mul_f32 v[72:73], v[72:73], v[222:223] op_sel_hi:[1,0]
	v_pk_mul_f32 v[74:75], v[74:75], v[222:223] op_sel_hi:[1,0]
	v_pk_mul_f32 v[68:69], v[68:69], v[222:223] op_sel_hi:[1,0]
	v_pk_mul_f32 v[70:71], v[70:71], v[222:223] op_sel_hi:[1,0]
	v_pk_mul_f32 v[72:73], v[152:153], v[72:73]
	v_pk_mul_f32 v[74:75], v[154:155], v[74:75]
	v_pk_mul_f32 v[68:69], v[156:157], v[68:69]
	v_pk_mul_f32 v[70:71], v[158:159], v[70:71]
	global_store_dwordx4 v185, v[72:75], s[66:67] offset:512
	global_store_dwordx4 v185, v[68:71], s[66:67] offset:528
	v_pk_mul_f32 v[64:65], v[64:65], v[226:227] op_sel_hi:[1,0]
	v_pk_mul_f32 v[66:67], v[66:67], v[226:227] op_sel_hi:[1,0]
	v_pk_mul_f32 v[60:61], v[60:61], v[226:227] op_sel_hi:[1,0]
	v_pk_mul_f32 v[62:63], v[62:63], v[226:227] op_sel_hi:[1,0]
	v_pk_mul_f32 v[64:65], v[144:145], v[64:65]
	v_pk_mul_f32 v[66:67], v[146:147], v[66:67]
	v_pk_mul_f32 v[60:61], v[148:149], v[60:61]
	v_pk_mul_f32 v[62:63], v[150:151], v[62:63]
	global_store_dwordx4 v190, v[64:67], s[66:67]
	global_store_dwordx4 v190, v[60:63], s[66:67] offset:16
	v_pk_mul_f32 v[56:57], v[56:57], v[226:227] op_sel_hi:[1,0]
	v_pk_mul_f32 v[58:59], v[58:59], v[226:227] op_sel_hi:[1,0]
	v_pk_mul_f32 v[52:53], v[52:53], v[226:227] op_sel_hi:[1,0]
	v_pk_mul_f32 v[54:55], v[54:55], v[226:227] op_sel_hi:[1,0]
	v_pk_mul_f32 v[56:57], v[152:153], v[56:57]
	v_pk_mul_f32 v[58:59], v[154:155], v[58:59]
	v_pk_mul_f32 v[52:53], v[156:157], v[52:53]
	v_pk_mul_f32 v[54:55], v[158:159], v[54:55]
	global_store_dwordx4 v190, v[56:59], s[66:67] offset:512
	global_store_dwordx4 v190, v[52:55], s[66:67] offset:528
	v_pk_mul_f32 v[48:49], v[48:49], v[230:231] op_sel_hi:[1,0]
	v_pk_mul_f32 v[50:51], v[50:51], v[230:231] op_sel_hi:[1,0]
	v_pk_mul_f32 v[44:45], v[44:45], v[230:231] op_sel_hi:[1,0]
	v_pk_mul_f32 v[46:47], v[46:47], v[230:231] op_sel_hi:[1,0]
	v_pk_mul_f32 v[48:49], v[144:145], v[48:49]
	v_pk_mul_f32 v[50:51], v[146:147], v[50:51]
	v_pk_mul_f32 v[44:45], v[148:149], v[44:45]
	v_pk_mul_f32 v[46:47], v[150:151], v[46:47]
	global_store_dwordx4 v191, v[48:51], s[66:67]
	global_store_dwordx4 v191, v[44:47], s[66:67] offset:16
	v_pk_mul_f32 v[40:41], v[40:41], v[230:231] op_sel_hi:[1,0]
	v_pk_mul_f32 v[42:43], v[42:43], v[230:231] op_sel_hi:[1,0]
	v_pk_mul_f32 v[36:37], v[36:37], v[230:231] op_sel_hi:[1,0]
	v_pk_mul_f32 v[38:39], v[38:39], v[230:231] op_sel_hi:[1,0]
	v_pk_mul_f32 v[40:41], v[152:153], v[40:41]
	v_pk_mul_f32 v[42:43], v[154:155], v[42:43]
	v_pk_mul_f32 v[36:37], v[156:157], v[36:37]
	v_pk_mul_f32 v[38:39], v[158:159], v[38:39]
	global_store_dwordx4 v191, v[40:43], s[66:67] offset:512
	global_store_dwordx4 v191, v[36:39], s[66:67] offset:528
	v_pk_mul_f32 v[32:33], v[32:33], v[234:235] op_sel_hi:[1,0]
	v_pk_mul_f32 v[34:35], v[34:35], v[234:235] op_sel_hi:[1,0]
	v_pk_mul_f32 v[28:29], v[28:29], v[234:235] op_sel_hi:[1,0]
	v_pk_mul_f32 v[30:31], v[30:31], v[234:235] op_sel_hi:[1,0]
	v_pk_mul_f32 v[32:33], v[144:145], v[32:33]
	v_pk_mul_f32 v[34:35], v[146:147], v[34:35]
	v_pk_mul_f32 v[28:29], v[148:149], v[28:29]
	v_pk_mul_f32 v[30:31], v[150:151], v[30:31]
	global_store_dwordx4 v200, v[32:35], s[66:67]
	global_store_dwordx4 v200, v[28:31], s[66:67] offset:16
	v_pk_mul_f32 v[24:25], v[24:25], v[234:235] op_sel_hi:[1,0]
	v_pk_mul_f32 v[26:27], v[26:27], v[234:235] op_sel_hi:[1,0]
	v_pk_mul_f32 v[20:21], v[20:21], v[234:235] op_sel_hi:[1,0]
	v_pk_mul_f32 v[22:23], v[22:23], v[234:235] op_sel_hi:[1,0]
	v_pk_mul_f32 v[24:25], v[152:153], v[24:25]
	v_pk_mul_f32 v[26:27], v[154:155], v[26:27]
	v_pk_mul_f32 v[20:21], v[156:157], v[20:21]
	v_pk_mul_f32 v[22:23], v[158:159], v[22:23]
	global_store_dwordx4 v200, v[24:27], s[66:67] offset:512
	global_store_dwordx4 v200, v[20:23], s[66:67] offset:528
	v_pk_mul_f32 v[16:17], v[16:17], v[238:239] op_sel_hi:[1,0]
	v_pk_mul_f32 v[18:19], v[18:19], v[238:239] op_sel_hi:[1,0]
	v_pk_mul_f32 v[12:13], v[12:13], v[238:239] op_sel_hi:[1,0]
	v_pk_mul_f32 v[14:15], v[14:15], v[238:239] op_sel_hi:[1,0]
	v_pk_mul_f32 v[16:17], v[144:145], v[16:17]
	v_pk_mul_f32 v[18:19], v[146:147], v[18:19]
	v_pk_mul_f32 v[12:13], v[148:149], v[12:13]
	v_pk_mul_f32 v[14:15], v[150:151], v[14:15]
	global_store_dwordx4 v201, v[16:19], s[66:67]
	global_store_dwordx4 v201, v[12:15], s[66:67] offset:16
	v_pk_mul_f32 v[8:9], v[8:9], v[238:239] op_sel_hi:[1,0]
	v_pk_mul_f32 v[10:11], v[10:11], v[238:239] op_sel_hi:[1,0]
	v_pk_mul_f32 v[4:5], v[4:5], v[238:239] op_sel_hi:[1,0]
	v_pk_mul_f32 v[6:7], v[6:7], v[238:239] op_sel_hi:[1,0]
	v_pk_mul_f32 v[8:9], v[152:153], v[8:9]
	v_pk_mul_f32 v[10:11], v[154:155], v[10:11]
	v_pk_mul_f32 v[4:5], v[156:157], v[4:5]
	v_pk_mul_f32 v[6:7], v[158:159], v[6:7]
	global_store_dwordx4 v201, v[8:11], s[66:67] offset:512
	global_store_dwordx4 v201, v[4:7], s[66:67] offset:528
	s_branch .LBB0_1375
;     __device__ __forceinline__ void emit(int row, int pn, int col0, float* v) const {
;     ...
;         case K_WO: case K_DN: {
;             const size_t o = ((size_t)grp * TG + row) * D + col0;
;             const f32x4 a0 = ldg<f32x4>(xi + o), a1 = ldg<f32x4>(xi + o + 4);
;             f32x4 r0, r1; r0.x = a0.x + v[0]; r0.y = a0.y + v[1]; r0.z = a0.z + v[2]; r0.w = a0.w + v[3]; r1.x = a1.x + v[4]; r1.y = a1.y + v[5]; r1.z = a1.z + v[6]; r1.w = a1.w + v[7];
;             stg<f32x4>(xo + o, r0); stg<f32x4>(xo + o + 4, r1);
;         } break;
.Lwo_epi:
	v_lshl_add_u32 v202, s43, 8, v186
	s_lshl_b32 s98, s42, 8
	v_or_b32_e32 v203, s98, v188
	v_lshl_add_u32 v242, v202, 10, v203
	v_add_u32_e32 v242, s0, v242
	v_lshlrev_b32_e32 v242, 2, v242
	v_mov_b32_e32 v182, v242
	v_add_u32_e32 v183, 0x10000, v242
	v_add_u32_e32 v184, 0x20000, v242
	v_add_u32_e32 v185, 0x30000, v242
	v_add_u32_e32 v190, 0x80000, v242
	v_add_u32_e32 v191, 0x90000, v242
	v_add_u32_e32 v200, 0xa0000, v242
	v_add_u32_e32 v201, 0xb0000, v242
	global_load_dwordx4 v[210:213], v182, s[74:75]
	global_load_dwordx4 v[214:217], v182, s[74:75] offset:16
	global_load_dwordx4 v[218:221], v182, s[74:75] offset:512
	global_load_dwordx4 v[222:225], v182, s[74:75] offset:528
	global_load_dwordx4 v[226:229], v183, s[74:75]
	global_load_dwordx4 v[230:233], v183, s[74:75] offset:16
	global_load_dwordx4 v[234:237], v183, s[74:75] offset:512
	global_load_dwordx4 v[238:241], v183, s[74:75] offset:528
	global_load_dwordx4 v[132:135], v184, s[74:75]
	global_load_dwordx4 v[136:139], v184, s[74:75] offset:16
	global_load_dwordx4 v[140:143], v184, s[74:75] offset:512
	global_load_dwordx4 v[144:147], v184, s[74:75] offset:528
	global_load_dwordx4 v[148:151], v185, s[74:75]
	global_load_dwordx4 v[152:155], v185, s[74:75] offset:16
	global_load_dwordx4 v[156:159], v185, s[74:75] offset:512
	global_load_dwordx4 v[160:163], v185, s[74:75] offset:528
	s_waitcnt vmcnt(8)
	v_pk_add_f32 v[128:129], v[128:129], v[210:211]
	v_pk_add_f32 v[130:131], v[130:131], v[212:213]
	v_pk_add_f32 v[124:125], v[124:125], v[214:215]
	v_pk_add_f32 v[126:127], v[126:127], v[216:217]
	v_pk_add_f32 v[120:121], v[120:121], v[218:219]
	v_pk_add_f32 v[122:123], v[122:123], v[220:221]
	v_pk_add_f32 v[116:117], v[116:117], v[222:223]
	v_pk_add_f32 v[118:119], v[118:119], v[224:225]
	v_pk_add_f32 v[112:113], v[112:113], v[226:227]
	v_pk_add_f32 v[114:115], v[114:115], v[228:229]
	v_pk_add_f32 v[108:109], v[108:109], v[230:231]
	v_pk_add_f32 v[110:111], v[110:111], v[232:233]
	v_pk_add_f32 v[104:105], v[104:105], v[234:235]
	v_pk_add_f32 v[106:107], v[106:107], v[236:237]
	v_pk_add_f32 v[100:101], v[100:101], v[238:239]
	v_pk_add_f32 v[102:103], v[102:103], v[240:241]
	global_load_dwordx4 v[210:213], v190, s[74:75]
	global_load_dwordx4 v[214:217], v190, s[74:75] offset:16
	global_load_dwordx4 v[218:221], v190, s[74:75] offset:512
	global_load_dwordx4 v[222:225], v190, s[74:75] offset:528
	global_load_dwordx4 v[226:229], v191, s[74:75]
	global_load_dwordx4 v[230:233], v191, s[74:75] offset:16
	global_load_dwordx4 v[234:237], v191, s[74:75] offset:512
	global_load_dwordx4 v[238:241], v191, s[74:75] offset:528
	s_waitcnt vmcnt(8)
	v_pk_add_f32 v[96:97], v[96:97], v[132:133]
	v_pk_add_f32 v[98:99], v[98:99], v[134:135]
	v_pk_add_f32 v[92:93], v[92:93], v[136:137]
	v_pk_add_f32 v[94:95], v[94:95], v[138:139]
	v_pk_add_f32 v[88:89], v[88:89], v[140:141]
	v_pk_add_f32 v[90:91], v[90:91], v[142:143]
	v_pk_add_f32 v[84:85], v[84:85], v[144:145]
	v_pk_add_f32 v[86:87], v[86:87], v[146:147]
	v_pk_add_f32 v[80:81], v[80:81], v[148:149]
	v_pk_add_f32 v[82:83], v[82:83], v[150:151]
	v_pk_add_f32 v[76:77], v[76:77], v[152:153]
	v_pk_add_f32 v[78:79], v[78:79], v[154:155]
	v_pk_add_f32 v[72:73], v[72:73], v[156:157]
	v_pk_add_f32 v[74:75], v[74:75], v[158:159]
	v_pk_add_f32 v[68:69], v[68:69], v[160:161]
	v_pk_add_f32 v[70:71], v[70:71], v[162:163]
	global_load_dwordx4 v[132:135], v200, s[74:75]
	global_load_dwordx4 v[136:139], v200, s[74:75] offset:16
	global_load_dwordx4 v[140:143], v200, s[74:75] offset:512
	global_load_dwordx4 v[144:147], v200, s[74:75] offset:528
	global_load_dwordx4 v[148:151], v201, s[74:75]
	global_load_dwordx4 v[152:155], v201, s[74:75] offset:16
	global_load_dwordx4 v[156:159], v201, s[74:75] offset:512
	global_load_dwordx4 v[160:163], v201, s[74:75] offset:528
	s_waitcnt vmcnt(8)
	v_pk_add_f32 v[64:65], v[64:65], v[210:211]
	v_pk_add_f32 v[66:67], v[66:67], v[212:213]
	v_pk_add_f32 v[60:61], v[60:61], v[214:215]
	v_pk_add_f32 v[62:63], v[62:63], v[216:217]
	v_pk_add_f32 v[56:57], v[56:57], v[218:219]
	v_pk_add_f32 v[58:59], v[58:59], v[220:221]
	v_pk_add_f32 v[52:53], v[52:53], v[222:223]
	v_pk_add_f32 v[54:55], v[54:55], v[224:225]
	v_pk_add_f32 v[48:49], v[48:49], v[226:227]
	v_pk_add_f32 v[50:51], v[50:51], v[228:229]
	v_pk_add_f32 v[44:45], v[44:45], v[230:231]
	v_pk_add_f32 v[46:47], v[46:47], v[232:233]
	v_pk_add_f32 v[40:41], v[40:41], v[234:235]
	v_pk_add_f32 v[42:43], v[42:43], v[236:237]
	v_pk_add_f32 v[36:37], v[36:37], v[238:239]
	v_pk_add_f32 v[38:39], v[38:39], v[240:241]
	s_waitcnt vmcnt(0)
; __device__ __forceinline__ void rmsnorm_rows(const float* x, const float* gain, bf16_t* o, int nrows, int gw, int ngw, int lane) {
;     ...
;         for (int j = 0; j < 4; ++j) { va[j] = ldg<f32x4>(xa + 64 * j); vb[j] = ldg<f32x4>(xb + 64 * j); }
; #pragma unroll
;         for (int j = 0; j < 4; ++j) { sa += (va[j].x * va[j].x + va[j].y * va[j].y) + (va[j].z * va[j].z + va[j].w * va[j].w); sb += (vb[j].x * vb[j].x + vb[j].y * vb[j].y) + (vb[j].z * vb[j].z + vb[j].w * vb[j].w); }
; #pragma unroll
;         for (int of = 1; of < 64; of <<= 1) { sa += __shfl_xor(sa, of); sb += __shfl_xor(sb, of); }
	v_pk_add_f32 v[32:33], v[32:33], v[132:133]
	v_pk_add_f32 v[34:35], v[34:35], v[134:135]
	v_pk_add_f32 v[28:29], v[28:29], v[136:137]
	v_pk_add_f32 v[30:31], v[30:31], v[138:139]
	v_pk_add_f32 v[24:25], v[24:25], v[140:141]
	v_pk_add_f32 v[26:27], v[26:27], v[142:143]
	v_pk_add_f32 v[20:21], v[20:21], v[144:145]
	v_pk_add_f32 v[22:23], v[22:23], v[146:147]
	v_pk_add_f32 v[16:17], v[16:17], v[148:149]
	v_pk_add_f32 v[18:19], v[18:19], v[150:151]
	v_pk_add_f32 v[12:13], v[12:13], v[152:153]
	v_pk_add_f32 v[14:15], v[14:15], v[154:155]
	v_pk_add_f32 v[8:9], v[8:9], v[156:157]
	v_pk_add_f32 v[10:11], v[10:11], v[158:159]
	v_pk_add_f32 v[4:5], v[4:5], v[160:161]
	v_pk_add_f32 v[6:7], v[6:7], v[162:163]
	v_pk_mul_f32 v[210:211], v[116:117], v[116:117]
	v_pk_fma_f32 v[210:211], v[118:119], v[118:119], v[210:211]
	v_pk_fma_f32 v[210:211], v[120:121], v[120:121], v[210:211]
	v_pk_fma_f32 v[210:211], v[122:123], v[122:123], v[210:211]
	v_pk_fma_f32 v[210:211], v[124:125], v[124:125], v[210:211]
	v_pk_fma_f32 v[210:211], v[126:127], v[126:127], v[210:211]
	v_pk_fma_f32 v[210:211], v[128:129], v[128:129], v[210:211]
	v_pk_fma_f32 v[210:211], v[130:131], v[130:131], v[210:211]
	v_pk_mul_f32 v[212:213], v[100:101], v[100:101]
	v_pk_fma_f32 v[212:213], v[102:103], v[102:103], v[212:213]
	v_pk_fma_f32 v[212:213], v[104:105], v[104:105], v[212:213]
	v_pk_fma_f32 v[212:213], v[106:107], v[106:107], v[212:213]
	v_pk_fma_f32 v[212:213], v[108:109], v[108:109], v[212:213]
	v_pk_fma_f32 v[212:213], v[110:111], v[110:111], v[212:213]
	v_pk_fma_f32 v[212:213], v[112:113], v[112:113], v[212:213]
	v_pk_fma_f32 v[212:213], v[114:115], v[114:115], v[212:213]
	v_pk_mul_f32 v[214:215], v[84:85], v[84:85]
	v_pk_fma_f32 v[214:215], v[86:87], v[86:87], v[214:215]
	v_pk_fma_f32 v[214:215], v[88:89], v[88:89], v[214:215]
	v_pk_fma_f32 v[214:215], v[90:91], v[90:91], v[214:215]
	v_pk_fma_f32 v[214:215], v[92:93], v[92:93], v[214:215]
	v_pk_fma_f32 v[214:215], v[94:95], v[94:95], v[214:215]
	v_pk_fma_f32 v[214:215], v[96:97], v[96:97], v[214:215]
	v_pk_fma_f32 v[214:215], v[98:99], v[98:99], v[214:215]
	v_pk_mul_f32 v[216:217], v[68:69], v[68:69]
	v_pk_fma_f32 v[216:217], v[70:71], v[70:71], v[216:217]
	v_pk_fma_f32 v[216:217], v[72:73], v[72:73], v[216:217]
	v_pk_fma_f32 v[216:217], v[74:75], v[74:75], v[216:217]
	v_pk_fma_f32 v[216:217], v[76:77], v[76:77], v[216:217]
	v_pk_fma_f32 v[216:217], v[78:79], v[78:79], v[216:217]
	v_pk_fma_f32 v[216:217], v[80:81], v[80:81], v[216:217]
	v_pk_fma_f32 v[216:217], v[82:83], v[82:83], v[216:217]
	v_pk_mul_f32 v[218:219], v[52:53], v[52:53]
	v_pk_fma_f32 v[218:219], v[54:55], v[54:55], v[218:219]
	v_pk_fma_f32 v[218:219], v[56:57], v[56:57], v[218:219]
	v_pk_fma_f32 v[218:219], v[58:59], v[58:59], v[218:219]
	v_pk_fma_f32 v[218:219], v[60:61], v[60:61], v[218:219]
	v_pk_fma_f32 v[218:219], v[62:63], v[62:63], v[218:219]
	v_pk_fma_f32 v[218:219], v[64:65], v[64:65], v[218:219]
	v_pk_fma_f32 v[218:219], v[66:67], v[66:67], v[218:219]
	v_pk_mul_f32 v[220:221], v[36:37], v[36:37]
	v_pk_fma_f32 v[220:221], v[38:39], v[38:39], v[220:221]
	v_pk_fma_f32 v[220:221], v[40:41], v[40:41], v[220:221]
	v_pk_fma_f32 v[220:221], v[42:43], v[42:43], v[220:221]
	v_pk_fma_f32 v[220:221], v[44:45], v[44:45], v[220:221]
	v_pk_fma_f32 v[220:221], v[46:47], v[46:47], v[220:221]
	v_pk_fma_f32 v[220:221], v[48:49], v[48:49], v[220:221]
	v_pk_fma_f32 v[220:221], v[50:51], v[50:51], v[220:221]
	v_pk_mul_f32 v[222:223], v[20:21], v[20:21]
	v_pk_fma_f32 v[222:223], v[22:23], v[22:23], v[222:223]
	v_pk_fma_f32 v[222:223], v[24:25], v[24:25], v[222:223]
	v_pk_fma_f32 v[222:223], v[26:27], v[26:27], v[222:223]
	v_pk_fma_f32 v[222:223], v[28:29], v[28:29], v[222:223]
	v_pk_fma_f32 v[222:223], v[30:31], v[30:31], v[222:223]
	v_pk_fma_f32 v[222:223], v[32:33], v[32:33], v[222:223]
	v_pk_fma_f32 v[222:223], v[34:35], v[34:35], v[222:223]
	v_pk_mul_f32 v[224:225], v[4:5], v[4:5]
	v_pk_fma_f32 v[224:225], v[6:7], v[6:7], v[224:225]
	v_pk_fma_f32 v[224:225], v[8:9], v[8:9], v[224:225]
	v_pk_fma_f32 v[224:225], v[10:11], v[10:11], v[224:225]
	v_pk_fma_f32 v[224:225], v[12:13], v[12:13], v[224:225]
	v_pk_fma_f32 v[224:225], v[14:15], v[14:15], v[224:225]
	v_pk_fma_f32 v[224:225], v[16:17], v[16:17], v[224:225]
	v_pk_fma_f32 v[224:225], v[18:19], v[18:19], v[224:225]
	v_add_f32_e32 v210, v210, v211
	v_add_f32_e32 v212, v212, v213
	v_add_f32_e32 v214, v214, v215
	v_add_f32_e32 v216, v216, v217
	v_add_f32_e32 v218, v218, v219
	v_add_f32_e32 v220, v220, v221
	v_add_f32_e32 v222, v222, v223
	v_add_f32_e32 v224, v224, v225
	v_lshrrev_b32_e32 v243, 4, v192
	v_and_b32_e32 v243, 15, v243
	v_lshlrev_b32_e32 v243, 2, v243
	v_lshl_add_u32 v243, v186, 6, v243
	v_add_u32_e32 v243, 0x20000, v243
	ds_write_b32 v243, v210
	ds_write_b32 v243, v212 offset:1024
	ds_write_b32 v243, v214 offset:2048
	ds_write_b32 v243, v216 offset:3072
	ds_write_b32 v243, v218 offset:8192
	ds_write_b32 v243, v220 offset:9216
	ds_write_b32 v243, v222 offset:10240
	ds_write_b32 v243, v224 offset:11264
	v_mov_b32_e32 v132, 0x25950
	ds_read_b64 v[132:133], v132
	s_waitcnt lgkmcnt(0)
	s_barrier
	v_readfirstlane_b32 s98, v132
	v_readfirstlane_b32 s99, v133
	v_readfirstlane_b32 s100, v192
	s_add_u32 s98, s98, 0x40000
	s_addc_u32 s99, s99, 0
	s_cmpk_gt_u32 s100, 0xff
	s_cbranch_scc1 .Lwo_nopart
	v_lshlrev_b32_e32 v0, 6, v192
	v_add_u32_e32 v0, 0x20000, v0
	ds_read_b128 v[226:229], v0
	ds_read_b128 v[230:233], v0 offset:16
	ds_read_b128 v[234:237], v0 offset:32
	ds_read_b128 v[238:241], v0 offset:48
	s_lshl_b32 s100, s42, 14
	s_lshl_b32 s101, s43, 8
	s_add_i32 s100, s100, s101
	v_add_u32_e32 v0, s100, v192
	v_lshlrev_b32_e32 v0, 2, v0
	s_waitcnt lgkmcnt(0)
	v_add_f32_e32 v226, v226, v227
	v_add_f32_e32 v226, v226, v228
	v_add_f32_e32 v226, v226, v229
	v_add_f32_e32 v226, v226, v230
	v_add_f32_e32 v226, v226, v231
	v_add_f32_e32 v226, v226, v232
	v_add_f32_e32 v226, v226, v233
	v_add_f32_e32 v226, v226, v234
	v_add_f32_e32 v226, v226, v235
	v_add_f32_e32 v226, v226, v236
	v_add_f32_e32 v226, v226, v237
	v_add_f32_e32 v226, v226, v238
	v_add_f32_e32 v226, v226, v239
	v_add_f32_e32 v226, v226, v240
	v_add_f32_e32 v226, v226, v241
	global_store_dword v0, v226, s[98:99] sc1

; __device__ __forceinline__ unsigned cvt_pk_bf16(float lo, float hi) { const f32x2 v = {lo, hi}; const bf16x2_native b = __builtin_convertvector(v, bf16x2_native); return __builtin_bit_cast(unsigned, b); }
; __device__ __forceinline__ void rmsnorm_rows(const float* x, const float* gain, bf16_t* o, int nrows, int gw, int ngw, int lane) {
;     ...
;         const float ra = rsqrtf(sa * (1.f / D) + 1e-6f), rbb = rsqrtf(sb * (1.f / D) + 1e-6f);
;         u32x2* oa = (u32x2*)(o + (size_t)r * D) + lane; u32x2* ob = (u32x2*)(o + (size_t)rb * D) + lane;
; #pragma unroll
;         for (int j = 0; j < 4; ++j) { u32x2 w; w.x = cvt_pk_bf16(va[j].x * ra * gv[j].x, va[j].y * ra * gv[j].y); w.y = cvt_pk_bf16(va[j].z * ra * gv[j].z, va[j].w * ra * gv[j].w); stg<u32x2>(oa + 64 * j, w); }
;     __device__ __forceinline__ void emit(int row, int pn, int col0, float* v) const {
;     ...
;         case K_WO: case K_DN: {
;             const size_t o = ((size_t)grp * TG + row) * D + col0;
;             const f32x4 a0 = ldg<f32x4>(xi + o), a1 = ldg<f32x4>(xi + o + 4);
;             f32x4 r0, r1; r0.x = a0.x + v[0]; r0.y = a0.y + v[1]; r0.z = a0.z + v[2]; r0.w = a0.w + v[3]; r1.x = a1.x + v[4]; r1.y = a1.y + v[5]; r1.z = a1.z + v[6]; r1.w = a1.w + v[7];
;             stg<f32x4>(xo + o, r0); stg<f32x4>(xo + o + 4, r1);
.Lwo_bw:
	s_barrier
	v_lshlrev_b32_e32 v136, 2, v202
	v_add_u32_e32 v137, 0x10000, v136
	v_add_u32_e32 v138, 0x20000, v136
	v_add_u32_e32 v139, 0x30000, v136
	global_load_dword v210, v136, s[98:99] sc1
	global_load_dword v211, v137, s[98:99] sc1
	global_load_dword v212, v138, s[98:99] sc1
	global_load_dword v213, v139, s[98:99] sc1
	global_load_dword v214, v136, s[98:99] offset:64 sc1
	global_load_dword v215, v137, s[98:99] offset:64 sc1
	global_load_dword v216, v138, s[98:99] offset:64 sc1
	global_load_dword v217, v139, s[98:99] offset:64 sc1
	global_load_dword v218, v136, s[98:99] offset:128 sc1
	global_load_dword v219, v137, s[98:99] offset:128 sc1
	global_load_dword v220, v138, s[98:99] offset:128 sc1
	global_load_dword v221, v139, s[98:99] offset:128 sc1
	global_load_dword v222, v136, s[98:99] offset:192 sc1
	global_load_dword v223, v137, s[98:99] offset:192 sc1
	global_load_dword v224, v138, s[98:99] offset:192 sc1
	global_load_dword v225, v139, s[98:99] offset:192 sc1
	global_load_dword v226, v136, s[98:99] offset:512 sc1
	global_load_dword v227, v137, s[98:99] offset:512 sc1
	global_load_dword v228, v138, s[98:99] offset:512 sc1
	global_load_dword v229, v139, s[98:99] offset:512 sc1
	global_load_dword v230, v136, s[98:99] offset:576 sc1
	global_load_dword v231, v137, s[98:99] offset:576 sc1
	global_load_dword v232, v138, s[98:99] offset:576 sc1
	global_load_dword v233, v139, s[98:99] offset:576 sc1
	global_load_dword v234, v136, s[98:99] offset:640 sc1
	global_load_dword v235, v137, s[98:99] offset:640 sc1
	global_load_dword v236, v138, s[98:99] offset:640 sc1
	global_load_dword v237, v139, s[98:99] offset:640 sc1
	global_load_dword v238, v136, s[98:99] offset:704 sc1
	global_load_dword v239, v137, s[98:99] offset:704 sc1
	global_load_dword v240, v138, s[98:99] offset:704 sc1
	global_load_dword v241, v139, s[98:99] offset:704 sc1
	v_mov_b32_e32 v0, 0x25918
	ds_read_b64 v[140:141], v0
	v_lshlrev_b32_e32 v0, 2, v203
	v_mov_b32_e32 v142, 0x358637bd
	s_waitcnt lgkmcnt(0)
	v_readfirstlane_b32 s100, v140
	v_readfirstlane_b32 s101, v141
	v_readlane_b32 s98, v255, 12
	s_cmpk_gt_u32 s98, 24
	s_cselect_b32 s98, 0x1000, 0
	s_add_u32 s100, s100, s98
	s_addc_u32 s101, s101, 0
	v_readfirstlane_b32 s98, v132
	v_readfirstlane_b32 s99, v133
	s_add_u32 s98, s98, 0x2d00000
	s_addc_u32 s99, s99, 0
	s_nop 1
	global_load_dwordx4 v[144:147], v0, s[100:101]
	global_load_dwordx4 v[148:151], v0, s[100:101] offset:16
	global_load_dwordx4 v[152:155], v0, s[100:101] offset:512
	global_load_dwordx4 v[156:159], v0, s[100:101] offset:528
	v_lshl_add_u32 v143, v202, 10, v203
	v_lshlrev_b32_e32 v143, 1, v143
	v_mov_b32_e32 v132, v143
	v_add_u32_e32 v133, 0x8000, v143
	v_add_u32_e32 v134, 0x10000, v143
	v_add_u32_e32 v135, 0x18000, v143
	v_add_u32_e32 v136, 0x40000, v143
	v_add_u32_e32 v137, 0x48000, v143
	v_add_u32_e32 v138, 0x50000, v143
	v_add_u32_e32 v139, 0x58000, v143
	s_waitcnt vmcnt(0)
	v_add_f32_e32 v210, v210, v211
	v_add_f32_e32 v210, v210, v212
	v_add_f32_e32 v210, v210, v213
	v_fmamk_f32 v210, v210, 0x3a800000, v142
	v_add_f32_e32 v214, v214, v215
	v_add_f32_e32 v214, v214, v216
	v_add_f32_e32 v214, v214, v217
	v_fmamk_f32 v214, v214, 0x3a800000, v142
	v_add_f32_e32 v218, v218, v219
	v_add_f32_e32 v218, v218, v220
	v_add_f32_e32 v218, v218, v221
	v_fmamk_f32 v218, v218, 0x3a800000, v142
	v_add_f32_e32 v222, v222, v223
	v_add_f32_e32 v222, v222, v224
	v_add_f32_e32 v222, v222, v225
	v_fmamk_f32 v222, v222, 0x3a800000, v142
	v_add_f32_e32 v226, v226, v227
	v_add_f32_e32 v226, v226, v228
	v_add_f32_e32 v226, v226, v229
	v_fmamk_f32 v226, v226, 0x3a800000, v142
	v_add_f32_e32 v230, v230, v231
	v_add_f32_e32 v230, v230, v232
	v_add_f32_e32 v230, v230, v233
	v_fmamk_f32 v230, v230, 0x3a800000, v142
	v_add_f32_e32 v234, v234, v235
	v_add_f32_e32 v234, v234, v236
	v_add_f32_e32 v234, v234, v237
	v_fmamk_f32 v234, v234, 0x3a800000, v142
	v_add_f32_e32 v238, v238, v239
	v_add_f32_e32 v238, v238, v240
	v_add_f32_e32 v238, v238, v241
	v_fmamk_f32 v238, v238, 0x3a800000, v142
	v_rsq_f32_e32 v210, v210
	v_rsq_f32_e32 v214, v214
	v_rsq_f32_e32 v218, v218
	v_rsq_f32_e32 v222, v222
	v_rsq_f32_e32 v226, v226
	v_rsq_f32_e32 v230, v230
	v_rsq_f32_e32 v234, v234
	v_rsq_f32_e32 v238, v238
	s_nop 0
	global_store_dwordx4 v182, v[128:131], s[66:67]
	global_store_dwordx4 v182, v[124:127], s[66:67] offset:16
	v_pk_mul_f32 v[212:213], v[128:129], v[210:211] op_sel_hi:[1,0]
	v_pk_mul_f32 v[216:217], v[130:131], v[210:211] op_sel_hi:[1,0]
	v_pk_mul_f32 v[220:221], v[124:125], v[210:211] op_sel_hi:[1,0]
	v_pk_mul_f32 v[224:225], v[126:127], v[210:211] op_sel_hi:[1,0]
	v_pk_mul_f32 v[212:213], v[144:145], v[212:213]
	v_pk_mul_f32 v[216:217], v[146:147], v[216:217]
	v_pk_mul_f32 v[220:221], v[148:149], v[220:221]
	v_pk_mul_f32 v[224:225], v[150:151], v[224:225]
	v_cvt_pk_bf16_f32 v160, v212, v213
	v_cvt_pk_bf16_f32 v161, v216, v217
	v_cvt_pk_bf16_f32 v162, v220, v221
	v_cvt_pk_bf16_f32 v163, v224, v225
	global_store_dwordx4 v132, v[160:163], s[98:99]
	global_store_dwordx4 v182, v[120:123], s[66:67] offset:512
	global_store_dwordx4 v182, v[116:119], s[66:67] offset:528
	v_pk_mul_f32 v[228:229], v[120:121], v[210:211] op_sel_hi:[1,0]
	v_pk_mul_f32 v[232:233], v[122:123], v[210:211] op_sel_hi:[1,0]
	v_pk_mul_f32 v[236:237], v[116:117], v[210:211] op_sel_hi:[1,0]
	v_pk_mul_f32 v[240:241], v[118:119], v[210:211] op_sel_hi:[1,0]
	v_pk_mul_f32 v[228:229], v[152:153], v[228:229]
	v_pk_mul_f32 v[232:233], v[154:155], v[232:233]
	v_pk_mul_f32 v[236:237], v[156:157], v[236:237]
	v_pk_mul_f32 v[240:241], v[158:159], v[240:241]
	v_cvt_pk_bf16_f32 v160, v228, v229
	v_cvt_pk_bf16_f32 v161, v232, v233
; __device__ __forceinline__ unsigned cvt_pk_bf16(float lo, float hi) { const f32x2 v = {lo, hi}; const bf16x2_native b = __builtin_convertvector(v, bf16x2_native); return __builtin_bit_cast(unsigned, b); }
; __device__ __forceinline__ void rmsnorm_rows(const float* x, const float* gain, bf16_t* o, int nrows, int gw, int ngw, int lane) {
;     ...
;         u32x2* oa = (u32x2*)(o + (size_t)r * D) + lane; u32x2* ob = (u32x2*)(o + (size_t)rb * D) + lane;
; #pragma unroll
;         for (int j = 0; j < 4; ++j) { u32x2 w; w.x = cvt_pk_bf16(va[j].x * ra * gv[j].x, va[j].y * ra * gv[j].y); w.y = cvt_pk_bf16(va[j].z * ra * gv[j].z, va[j].w * ra * gv[j].w); stg<u32x2>(oa + 64 * j, w); }
;         if (has2) {
; #pragma unroll
;             for (int j = 0; j < 4; ++j) { u32x2 w; w.x = cvt_pk_bf16(vb[j].x * rbb * gv[j].x, vb[j].y * rbb * gv[j].y); w.y = cvt_pk_bf16(vb[j].z * rbb * gv[j].z, vb[j].w * rbb * gv[j].w); stg<u32x2>(ob + 64 * j, w); } }
	v_cvt_pk_bf16_f32 v162, v236, v237
	v_cvt_pk_bf16_f32 v163, v240, v241
	global_store_dwordx4 v132, v[160:163], s[98:99] offset:256
	global_store_dwordx4 v183, v[112:115], s[66:67]
	global_store_dwordx4 v183, v[108:111], s[66:67] offset:16
	v_pk_mul_f32 v[212:213], v[112:113], v[214:215] op_sel_hi:[1,0]
	v_pk_mul_f32 v[216:217], v[114:115], v[214:215] op_sel_hi:[1,0]
	v_pk_mul_f32 v[220:221], v[108:109], v[214:215] op_sel_hi:[1,0]
	v_pk_mul_f32 v[224:225], v[110:111], v[214:215] op_sel_hi:[1,0]
	v_pk_mul_f32 v[212:213], v[144:145], v[212:213]
	v_pk_mul_f32 v[216:217], v[146:147], v[216:217]
	v_pk_mul_f32 v[220:221], v[148:149], v[220:221]
	v_pk_mul_f32 v[224:225], v[150:151], v[224:225]
	v_cvt_pk_bf16_f32 v160, v212, v213
	v_cvt_pk_bf16_f32 v161, v216, v217
	v_cvt_pk_bf16_f32 v162, v220, v221
	v_cvt_pk_bf16_f32 v163, v224, v225
	global_store_dwordx4 v133, v[160:163], s[98:99]
	global_store_dwordx4 v183, v[104:107], s[66:67] offset:512
	global_store_dwordx4 v183, v[100:103], s[66:67] offset:528
	v_pk_mul_f32 v[228:229], v[104:105], v[214:215] op_sel_hi:[1,0]
	v_pk_mul_f32 v[232:233], v[106:107], v[214:215] op_sel_hi:[1,0]
	v_pk_mul_f32 v[236:237], v[100:101], v[214:215] op_sel_hi:[1,0]
	v_pk_mul_f32 v[240:241], v[102:103], v[214:215] op_sel_hi:[1,0]
	v_pk_mul_f32 v[228:229], v[152:153], v[228:229]
	v_pk_mul_f32 v[232:233], v[154:155], v[232:233]
	v_pk_mul_f32 v[236:237], v[156:157], v[236:237]
	v_pk_mul_f32 v[240:241], v[158:159], v[240:241]
	v_cvt_pk_bf16_f32 v160, v228, v229
	v_cvt_pk_bf16_f32 v161, v232, v233
	v_cvt_pk_bf16_f32 v162, v236, v237
	v_cvt_pk_bf16_f32 v163, v240, v241
	global_store_dwordx4 v133, v[160:163], s[98:99] offset:256
	global_store_dwordx4 v184, v[96:99], s[66:67]
	global_store_dwordx4 v184, v[92:95], s[66:67] offset:16
	v_pk_mul_f32 v[212:213], v[96:97], v[218:219] op_sel_hi:[1,0]
	v_pk_mul_f32 v[216:217], v[98:99], v[218:219] op_sel_hi:[1,0]
	v_pk_mul_f32 v[220:221], v[92:93], v[218:219] op_sel_hi:[1,0]
	v_pk_mul_f32 v[224:225], v[94:95], v[218:219] op_sel_hi:[1,0]
	v_pk_mul_f32 v[212:213], v[144:145], v[212:213]
	v_pk_mul_f32 v[216:217], v[146:147], v[216:217]
	v_pk_mul_f32 v[220:221], v[148:149], v[220:221]
	v_pk_mul_f32 v[224:225], v[150:151], v[224:225]
	v_cvt_pk_bf16_f32 v160, v212, v213
	v_cvt_pk_bf16_f32 v161, v216, v217
	v_cvt_pk_bf16_f32 v162, v220, v221
	v_cvt_pk_bf16_f32 v163, v224, v225
	global_store_dwordx4 v134, v[160:163], s[98:99]
	global_store_dwordx4 v184, v[88:91], s[66:67] offset:512
	global_store_dwordx4 v184, v[84:87], s[66:67] offset:528
	v_pk_mul_f32 v[228:229], v[88:89], v[218:219] op_sel_hi:[1,0]
	v_pk_mul_f32 v[232:233], v[90:91], v[218:219] op_sel_hi:[1,0]
	v_pk_mul_f32 v[236:237], v[84:85], v[218:219] op_sel_hi:[1,0]
	v_pk_mul_f32 v[240:241], v[86:87], v[218:219] op_sel_hi:[1,0]
	v_pk_mul_f32 v[228:229], v[152:153], v[228:229]
	v_pk_mul_f32 v[232:233], v[154:155], v[232:233]
	v_pk_mul_f32 v[236:237], v[156:157], v[236:237]
	v_pk_mul_f32 v[240:241], v[158:159], v[240:241]
	v_cvt_pk_bf16_f32 v160, v228, v229
	v_cvt_pk_bf16_f32 v161, v232, v233
	v_cvt_pk_bf16_f32 v162, v236, v237
	v_cvt_pk_bf16_f32 v163, v240, v241
	global_store_dwordx4 v134, v[160:163], s[98:99] offset:256
	global_store_dwordx4 v185, v[80:83], s[66:67]
	global_store_dwordx4 v185, v[76:79], s[66:67] offset:16
	v_pk_mul_f32 v[212:213], v[80:81], v[222:223] op_sel_hi:[1,0]
	v_pk_mul_f32 v[216:217], v[82:83], v[222:223] op_sel_hi:[1,0]
	v_pk_mul_f32 v[220:221], v[76:77], v[222:223] op_sel_hi:[1,0]
	v_pk_mul_f32 v[224:225], v[78:79], v[222:223] op_sel_hi:[1,0]
	v_pk_mul_f32 v[212:213], v[144:145], v[212:213]
	v_pk_mul_f32 v[216:217], v[146:147], v[216:217]
	v_pk_mul_f32 v[220:221], v[148:149], v[220:221]
	v_pk_mul_f32 v[224:225], v[150:151], v[224:225]
	v_cvt_pk_bf16_f32 v160, v212, v213
	v_cvt_pk_bf16_f32 v161, v216, v217
	v_cvt_pk_bf16_f32 v162, v220, v221
	v_cvt_pk_bf16_f32 v163, v224, v225
	global_store_dwordx4 v135, v[160:163], s[98:99]
	global_store_dwordx4 v185, v[72:75], s[66:67] offset:512
	global_store_dwordx4 v185, v[68:71], s[66:67] offset:528
	v_pk_mul_f32 v[228:229], v[72:73], v[222:223] op_sel_hi:[1,0]
	v_pk_mul_f32 v[232:233], v[74:75], v[222:223] op_sel_hi:[1,0]
	v_pk_mul_f32 v[236:237], v[68:69], v[222:223] op_sel_hi:[1,0]
	v_pk_mul_f32 v[240:241], v[70:71], v[222:223] op_sel_hi:[1,0]
	v_pk_mul_f32 v[228:229], v[152:153], v[228:229]
	v_pk_mul_f32 v[232:233], v[154:155], v[232:233]
	v_pk_mul_f32 v[236:237], v[156:157], v[236:237]
	v_pk_mul_f32 v[240:241], v[158:159], v[240:241]
	v_cvt_pk_bf16_f32 v160, v228, v229
	v_cvt_pk_bf16_f32 v161, v232, v233
	v_cvt_pk_bf16_f32 v162, v236, v237
	v_cvt_pk_bf16_f32 v163, v240, v241
	global_store_dwordx4 v135, v[160:163], s[98:99] offset:256
	global_store_dwordx4 v190, v[64:67], s[66:67]
	global_store_dwordx4 v190, v[60:63], s[66:67] offset:16
	v_pk_mul_f32 v[212:213], v[64:65], v[226:227] op_sel_hi:[1,0]
	v_pk_mul_f32 v[216:217], v[66:67], v[226:227] op_sel_hi:[1,0]
	v_pk_mul_f32 v[220:221], v[60:61], v[226:227] op_sel_hi:[1,0]
	v_pk_mul_f32 v[224:225], v[62:63], v[226:227] op_sel_hi:[1,0]
	v_pk_mul_f32 v[212:213], v[144:145], v[212:213]
	v_pk_mul_f32 v[216:217], v[146:147], v[216:217]
	v_pk_mul_f32 v[220:221], v[148:149], v[220:221]
	v_pk_mul_f32 v[224:225], v[150:151], v[224:225]
	v_cvt_pk_bf16_f32 v160, v212, v213
	v_cvt_pk_bf16_f32 v161, v216, v217
	v_cvt_pk_bf16_f32 v162, v220, v221
	v_cvt_pk_bf16_f32 v163, v224, v225
	global_store_dwordx4 v136, v[160:163], s[98:99]
; __device__ __forceinline__ unsigned cvt_pk_bf16(float lo, float hi) { const f32x2 v = {lo, hi}; const bf16x2_native b = __builtin_convertvector(v, bf16x2_native); return __builtin_bit_cast(unsigned, b); }
; __device__ __forceinline__ void rmsnorm_rows(const float* x, const float* gain, bf16_t* o, int nrows, int gw, int ngw, int lane) {
;     ...
;         u32x2* oa = (u32x2*)(o + (size_t)r * D) + lane; u32x2* ob = (u32x2*)(o + (size_t)rb * D) + lane;
; #pragma unroll
;         for (int j = 0; j < 4; ++j) { u32x2 w; w.x = cvt_pk_bf16(va[j].x * ra * gv[j].x, va[j].y * ra * gv[j].y); w.y = cvt_pk_bf16(va[j].z * ra * gv[j].z, va[j].w * ra * gv[j].w); stg<u32x2>(oa + 64 * j, w); }
;         if (has2) {
; #pragma unroll
;             for (int j = 0; j < 4; ++j) { u32x2 w; w.x = cvt_pk_bf16(vb[j].x * rbb * gv[j].x, vb[j].y * rbb * gv[j].y); w.y = cvt_pk_bf16(vb[j].z * rbb * gv[j].z, vb[j].w * rbb * gv[j].w); stg<u32x2>(ob + 64 * j, w); } }
	global_store_dwordx4 v190, v[56:59], s[66:67] offset:512
	global_store_dwordx4 v190, v[52:55], s[66:67] offset:528
	v_pk_mul_f32 v[228:229], v[56:57], v[226:227] op_sel_hi:[1,0]
	v_pk_mul_f32 v[232:233], v[58:59], v[226:227] op_sel_hi:[1,0]
	v_pk_mul_f32 v[236:237], v[52:53], v[226:227] op_sel_hi:[1,0]
	v_pk_mul_f32 v[240:241], v[54:55], v[226:227] op_sel_hi:[1,0]
	v_pk_mul_f32 v[228:229], v[152:153], v[228:229]
	v_pk_mul_f32 v[232:233], v[154:155], v[232:233]
	v_pk_mul_f32 v[236:237], v[156:157], v[236:237]
	v_pk_mul_f32 v[240:241], v[158:159], v[240:241]
	v_cvt_pk_bf16_f32 v160, v228, v229
	v_cvt_pk_bf16_f32 v161, v232, v233
	v_cvt_pk_bf16_f32 v162, v236, v237
	v_cvt_pk_bf16_f32 v163, v240, v241
	global_store_dwordx4 v136, v[160:163], s[98:99] offset:256
	global_store_dwordx4 v191, v[48:51], s[66:67]
	global_store_dwordx4 v191, v[44:47], s[66:67] offset:16
	v_pk_mul_f32 v[212:213], v[48:49], v[230:231] op_sel_hi:[1,0]
	v_pk_mul_f32 v[216:217], v[50:51], v[230:231] op_sel_hi:[1,0]
	v_pk_mul_f32 v[220:221], v[44:45], v[230:231] op_sel_hi:[1,0]
	v_pk_mul_f32 v[224:225], v[46:47], v[230:231] op_sel_hi:[1,0]
	v_pk_mul_f32 v[212:213], v[144:145], v[212:213]
	v_pk_mul_f32 v[216:217], v[146:147], v[216:217]
	v_pk_mul_f32 v[220:221], v[148:149], v[220:221]
	v_pk_mul_f32 v[224:225], v[150:151], v[224:225]
	v_cvt_pk_bf16_f32 v160, v212, v213
	v_cvt_pk_bf16_f32 v161, v216, v217
	v_cvt_pk_bf16_f32 v162, v220, v221
	v_cvt_pk_bf16_f32 v163, v224, v225
	global_store_dwordx4 v137, v[160:163], s[98:99]
	global_store_dwordx4 v191, v[40:43], s[66:67] offset:512
	global_store_dwordx4 v191, v[36:39], s[66:67] offset:528
	v_pk_mul_f32 v[228:229], v[40:41], v[230:231] op_sel_hi:[1,0]
	v_pk_mul_f32 v[232:233], v[42:43], v[230:231] op_sel_hi:[1,0]
	v_pk_mul_f32 v[236:237], v[36:37], v[230:231] op_sel_hi:[1,0]
	v_pk_mul_f32 v[240:241], v[38:39], v[230:231] op_sel_hi:[1,0]
	v_pk_mul_f32 v[228:229], v[152:153], v[228:229]
	v_pk_mul_f32 v[232:233], v[154:155], v[232:233]
	v_pk_mul_f32 v[236:237], v[156:157], v[236:237]
	v_pk_mul_f32 v[240:241], v[158:159], v[240:241]
	v_cvt_pk_bf16_f32 v160, v228, v229
	v_cvt_pk_bf16_f32 v161, v232, v233
	v_cvt_pk_bf16_f32 v162, v236, v237
	v_cvt_pk_bf16_f32 v163, v240, v241
	global_store_dwordx4 v137, v[160:163], s[98:99] offset:256
	global_store_dwordx4 v200, v[32:35], s[66:67]
	global_store_dwordx4 v200, v[28:31], s[66:67] offset:16
	v_pk_mul_f32 v[212:213], v[32:33], v[234:235] op_sel_hi:[1,0]
	v_pk_mul_f32 v[216:217], v[34:35], v[234:235] op_sel_hi:[1,0]
	v_pk_mul_f32 v[220:221], v[28:29], v[234:235] op_sel_hi:[1,0]
	v_pk_mul_f32 v[224:225], v[30:31], v[234:235] op_sel_hi:[1,0]
	v_pk_mul_f32 v[212:213], v[144:145], v[212:213]
	v_pk_mul_f32 v[216:217], v[146:147], v[216:217]
	v_pk_mul_f32 v[220:221], v[148:149], v[220:221]
	v_pk_mul_f32 v[224:225], v[150:151], v[224:225]
	v_cvt_pk_bf16_f32 v160, v212, v213
	v_cvt_pk_bf16_f32 v161, v216, v217
	v_cvt_pk_bf16_f32 v162, v220, v221
	v_cvt_pk_bf16_f32 v163, v224, v225
	global_store_dwordx4 v138, v[160:163], s[98:99]
	global_store_dwordx4 v200, v[24:27], s[66:67] offset:512
	global_store_dwordx4 v200, v[20:23], s[66:67] offset:528
	v_pk_mul_f32 v[228:229], v[24:25], v[234:235] op_sel_hi:[1,0]
	v_pk_mul_f32 v[232:233], v[26:27], v[234:235] op_sel_hi:[1,0]
	v_pk_mul_f32 v[236:237], v[20:21], v[234:235] op_sel_hi:[1,0]
	v_pk_mul_f32 v[240:241], v[22:23], v[234:235] op_sel_hi:[1,0]
	v_pk_mul_f32 v[228:229], v[152:153], v[228:229]
	v_pk_mul_f32 v[232:233], v[154:155], v[232:233]
	v_pk_mul_f32 v[236:237], v[156:157], v[236:237]
	v_pk_mul_f32 v[240:241], v[158:159], v[240:241]
	v_cvt_pk_bf16_f32 v160, v228, v229
	v_cvt_pk_bf16_f32 v161, v232, v233
	v_cvt_pk_bf16_f32 v162, v236, v237
	v_cvt_pk_bf16_f32 v163, v240, v241
	global_store_dwordx4 v138, v[160:163], s[98:99] offset:256
	global_store_dwordx4 v201, v[16:19], s[66:67]
	global_store_dwordx4 v201, v[12:15], s[66:67] offset:16
	v_pk_mul_f32 v[212:213], v[16:17], v[238:239] op_sel_hi:[1,0]
	v_pk_mul_f32 v[216:217], v[18:19], v[238:239] op_sel_hi:[1,0]
	v_pk_mul_f32 v[220:221], v[12:13], v[238:239] op_sel_hi:[1,0]
	v_pk_mul_f32 v[224:225], v[14:15], v[238:239] op_sel_hi:[1,0]
	v_pk_mul_f32 v[212:213], v[144:145], v[212:213]
	v_pk_mul_f32 v[216:217], v[146:147], v[216:217]
	v_pk_mul_f32 v[220:221], v[148:149], v[220:221]
	v_pk_mul_f32 v[224:225], v[150:151], v[224:225]
	v_cvt_pk_bf16_f32 v160, v212, v213
	v_cvt_pk_bf16_f32 v161, v216, v217
	v_cvt_pk_bf16_f32 v162, v220, v221
	v_cvt_pk_bf16_f32 v163, v224, v225
	global_store_dwordx4 v139, v[160:163], s[98:99]
	global_store_dwordx4 v201, v[8:11], s[66:67] offset:512
	global_store_dwordx4 v201, v[4:7], s[66:67] offset:528
	v_pk_mul_f32 v[228:229], v[8:9], v[238:239] op_sel_hi:[1,0]
	v_pk_mul_f32 v[232:233], v[10:11], v[238:239] op_sel_hi:[1,0]
	v_pk_mul_f32 v[236:237], v[4:5], v[238:239] op_sel_hi:[1,0]
	v_pk_mul_f32 v[240:241], v[6:7], v[238:239] op_sel_hi:[1,0]
	v_pk_mul_f32 v[228:229], v[152:153], v[228:229]
	v_pk_mul_f32 v[232:233], v[154:155], v[232:233]
	v_pk_mul_f32 v[236:237], v[156:157], v[236:237]
	v_pk_mul_f32 v[240:241], v[158:159], v[240:241]
	v_cvt_pk_bf16_f32 v160, v228, v229
	v_cvt_pk_bf16_f32 v161, v232, v233
	v_cvt_pk_bf16_f32 v162, v236, v237
	v_cvt_pk_bf16_f32 v163, v240, v241
	global_store_dwordx4 v139, v[160:163], s[98:99] offset:256
	s_branch .LBB0_1375
.Lfx_tramp:
	s_branch .LBB0_1525
.Lfx_t8:
	s_branch .LBB0_8
.Lfx_t9:
	s_branch .LBB0_9
